# v83 + GEMM tile start: accumulators zeroed with 64 v_mov_b64 instead of 128 v_mov_b32
# speedup vs baseline: 1.0201x; 1.0201x over previous
; template <class Epi, class Sched, bool ALIGN_EPI = false, bool SP2 = false>
; __device__ __forceinline__ void gemm_phase(PG8_LAS unsigned char* lds, const Gemm g, const Sched& S, const Epi& E) {
;     ...
;         const bool has_next = S.next(ui + 1, nxt);
;         const char* nA = has_next ? (const char*)g.A + (size_t)nxt.pm * tstep : cA; const char* nB = has_next ? (const char*)g.Bt + (size_t)nxt.pn * tstep : cB;
;         for (int t = 0; t < nt; t += 2) {
;             const bool last = (t == nt - 2);
;             const char* a1 = cA + (size_t)(t + 1) * kstep;
;             const char* a2 = last ? nA : cA + (size_t)(t + 2) * kstep; const char* b2 = last ? nB : cB + (size_t)(t + 2) * kstep;
;     ...
; #pragma unroll
;         for (int a = 0; a < 2; ++a)
; #pragma unroll
;             for (int b = 0; b < 2; ++b)
; #pragma unroll
;                 for (int m = 0; m < 4; ++m)
; #pragma unroll
;                     for (int n = 0; n < 2; ++n) acc[a][b][m][n] = (f32x4){0.f, 0.f, 0.f, 0.f};
.LBB0_99:
	s_ashr_i32 s21, s20, 31
	s_lshl_b64 s[24:25], s[20:21], 19
	s_add_u32 s24, s35, s24
	s_addc_u32 s25, s38, s25
	s_and_b64 s[26:27], s[4:5], exec
	s_cselect_b32 s3, s25, s9
	s_cselect_b32 s7, s24, s8
	s_ashr_i32 s23, s22, 31
	s_lshl_b64 s[26:27], s[22:23], 19
	s_add_u32 s26, s39, s26
	s_addc_u32 s27, s40, s27
	s_and_b64 s[30:31], s[4:5], exec
	s_cselect_b32 s11, s27, s29
	s_cselect_b32 s21, s26, s28
	s_add_u32 s8, s8, 0x40080
	s_addc_u32 s9, s9, 0
	s_add_u32 s23, s28, 0x100
	v_mov_b64_e32 v[4:5], 0
	s_addc_u32 s44, s29, 0
	s_mov_b32 s45, -2
	v_mov_b64_e32 v[6:7], 0
	v_mov_b64_e32 v[8:9], 0
	v_mov_b64_e32 v[10:11], 0
	v_mov_b64_e32 v[12:13], 0
	v_mov_b64_e32 v[14:15], 0
	v_mov_b64_e32 v[16:17], 0
	v_mov_b64_e32 v[18:19], 0
	v_mov_b64_e32 v[20:21], 0
	v_mov_b64_e32 v[22:23], 0
	v_mov_b64_e32 v[24:25], 0
	v_mov_b64_e32 v[26:27], 0
	v_mov_b64_e32 v[28:29], 0
	v_mov_b64_e32 v[30:31], 0
	v_mov_b64_e32 v[32:33], 0
	v_mov_b64_e32 v[34:35], 0
	v_mov_b64_e32 v[36:37], 0
	v_mov_b64_e32 v[38:39], 0
	v_mov_b64_e32 v[40:41], 0
	v_mov_b64_e32 v[42:43], 0
	v_mov_b64_e32 v[44:45], 0
	v_mov_b64_e32 v[46:47], 0
	v_mov_b64_e32 v[48:49], 0
	v_mov_b64_e32 v[50:51], 0
	v_mov_b64_e32 v[52:53], 0
	v_mov_b64_e32 v[54:55], 0
	v_mov_b64_e32 v[56:57], 0
	v_mov_b64_e32 v[58:59], 0
	v_mov_b64_e32 v[60:61], 0
	v_mov_b64_e32 v[62:63], 0
	v_mov_b64_e32 v[64:65], 0
	v_mov_b64_e32 v[66:67], 0
	v_mov_b64_e32 v[68:69], 0
	v_mov_b64_e32 v[70:71], 0
	v_mov_b64_e32 v[72:73], 0
	v_mov_b64_e32 v[74:75], 0
	v_mov_b64_e32 v[76:77], 0
	v_mov_b64_e32 v[78:79], 0
	v_mov_b64_e32 v[80:81], 0
	v_mov_b64_e32 v[82:83], 0
	v_mov_b64_e32 v[84:85], 0
	v_mov_b64_e32 v[86:87], 0
	v_mov_b64_e32 v[88:89], 0
	v_mov_b64_e32 v[90:91], 0
	v_mov_b64_e32 v[92:93], 0
	v_mov_b64_e32 v[94:95], 0
	v_mov_b64_e32 v[96:97], 0
	v_mov_b64_e32 v[98:99], 0
	v_mov_b64_e32 v[100:101], 0
	v_mov_b64_e32 v[102:103], 0
	v_mov_b64_e32 v[104:105], 0
	v_mov_b64_e32 v[106:107], 0
	v_mov_b64_e32 v[108:109], 0
	v_mov_b64_e32 v[110:111], 0
	v_mov_b64_e32 v[112:113], 0
	v_mov_b64_e32 v[114:115], 0
	v_mov_b64_e32 v[116:117], 0
	v_mov_b64_e32 v[118:119], 0
	v_mov_b64_e32 v[120:121], 0
	v_mov_b64_e32 v[122:123], 0
	v_mov_b64_e32 v[124:125], 0
	v_mov_b64_e32 v[126:127], 0
	v_mov_b64_e32 v[128:129], 0
	v_mov_b64_e32 v[130:131], 0

; template <class Epi, class Sched, bool ALIGN_EPI = false, bool SP2 = false>
; __device__ __forceinline__ void gemm_phase(PG8_LAS unsigned char* lds, const Gemm g, const Sched& S, const Epi& E) {
;     ...
;         const bool has_next = S.next(ui + 1, nxt);
;         const char* nA = has_next ? (const char*)g.A + (size_t)nxt.pm * tstep : cA; const char* nB = has_next ? (const char*)g.Bt + (size_t)nxt.pn * tstep : cB;
;         for (int t = 0; t < nt; t += 2) {
;             const bool last = (t == nt - 2);
;             const char* a1 = cA + (size_t)(t + 1) * kstep;
;             const char* a2 = last ? nA : cA + (size_t)(t + 2) * kstep; const char* b2 = last ? nB : cB + (size_t)(t + 2) * kstep;
;     ...
; #pragma unroll
;         for (int a = 0; a < 2; ++a)
; #pragma unroll
;             for (int b = 0; b < 2; ++b)
; #pragma unroll
;                 for (int m = 0; m < 4; ++m)
; #pragma unroll
;                     for (int n = 0; n < 2; ++n) acc[a][b][m][n] = (f32x4){0.f, 0.f, 0.f, 0.f};
.LBB0_328:
	s_ashr_i32 s17, s16, 31
	s_lshl_b64 s[20:21], s[16:17], 19
	s_add_u32 s20, s37, s20
	s_addc_u32 s21, s38, s21
	s_and_b64 s[22:23], s[6:7], exec
	s_cselect_b32 s3, s21, s29
	s_cselect_b32 s17, s20, s28
	s_ashr_i32 s19, s18, 31
	s_lshl_b64 s[22:23], s[18:19], 19
	s_add_u32 s22, s39, s22
	s_addc_u32 s23, s40, s23
	s_and_b64 s[34:35], s[6:7], exec
	s_cselect_b32 s19, s23, s31
	s_cselect_b32 s25, s22, s30
	s_add_u32 s28, s28, 0x40080
	s_addc_u32 s29, s29, 0
	s_add_u32 s27, s30, 0x100
	v_mov_b64_e32 v[4:5], 0
	s_addc_u32 s44, s31, 0
	s_mov_b32 s45, -2
	v_mov_b64_e32 v[6:7], 0
	v_mov_b64_e32 v[8:9], 0
	v_mov_b64_e32 v[10:11], 0
	v_mov_b64_e32 v[12:13], 0
	v_mov_b64_e32 v[14:15], 0
	v_mov_b64_e32 v[16:17], 0
	v_mov_b64_e32 v[18:19], 0
	v_mov_b64_e32 v[20:21], 0
	v_mov_b64_e32 v[22:23], 0
	v_mov_b64_e32 v[24:25], 0
	v_mov_b64_e32 v[26:27], 0
	v_mov_b64_e32 v[28:29], 0
	v_mov_b64_e32 v[30:31], 0
	v_mov_b64_e32 v[32:33], 0
	v_mov_b64_e32 v[34:35], 0
	v_mov_b64_e32 v[36:37], 0
	v_mov_b64_e32 v[38:39], 0
	v_mov_b64_e32 v[40:41], 0
	v_mov_b64_e32 v[42:43], 0
	v_mov_b64_e32 v[44:45], 0
	v_mov_b64_e32 v[46:47], 0
	v_mov_b64_e32 v[48:49], 0
	v_mov_b64_e32 v[50:51], 0
	v_mov_b64_e32 v[52:53], 0
	v_mov_b64_e32 v[54:55], 0
	v_mov_b64_e32 v[56:57], 0
	v_mov_b64_e32 v[58:59], 0
	v_mov_b64_e32 v[60:61], 0
	v_mov_b64_e32 v[62:63], 0
	v_mov_b64_e32 v[64:65], 0
	v_mov_b64_e32 v[66:67], 0
	v_mov_b64_e32 v[68:69], 0
	v_mov_b64_e32 v[70:71], 0
	v_mov_b64_e32 v[72:73], 0
	v_mov_b64_e32 v[74:75], 0
	s_waitcnt vmcnt(0)
	v_mov_b64_e32 v[76:77], 0
	v_mov_b64_e32 v[78:79], 0
	v_mov_b64_e32 v[80:81], 0
	v_mov_b64_e32 v[82:83], 0
	v_mov_b64_e32 v[84:85], 0
	v_mov_b64_e32 v[86:87], 0
	v_mov_b64_e32 v[88:89], 0
	v_mov_b64_e32 v[90:91], 0
	v_mov_b64_e32 v[92:93], 0
	v_mov_b64_e32 v[94:95], 0
	v_mov_b64_e32 v[96:97], 0
	v_mov_b64_e32 v[98:99], 0
	v_mov_b64_e32 v[100:101], 0
	v_mov_b64_e32 v[102:103], 0
	v_mov_b64_e32 v[104:105], 0
	v_mov_b64_e32 v[106:107], 0
	v_mov_b64_e32 v[116:117], 0
	v_mov_b64_e32 v[118:119], 0
	v_mov_b64_e32 v[120:121], 0
	v_mov_b64_e32 v[122:123], 0
	v_mov_b64_e32 v[136:137], 0
	v_mov_b64_e32 v[138:139], 0
	v_mov_b64_e32 v[144:145], 0
	v_mov_b64_e32 v[146:147], 0
	v_mov_b64_e32 v[152:153], 0
	v_mov_b64_e32 v[154:155], 0
	v_mov_b64_e32 v[160:161], 0
	v_mov_b64_e32 v[162:163], 0

; template <class Epi, class Sched, bool ALIGN_EPI = false, bool SP2 = false>
; __device__ __forceinline__ void gemm_phase(PG8_LAS unsigned char* lds, const Gemm g, const Sched& S, const Epi& E) {
;     ...
;         const bool has_next = S.next(ui + 1, nxt);
;         const char* nA = has_next ? (const char*)g.A + (size_t)nxt.pm * tstep : cA; const char* nB = has_next ? (const char*)g.Bt + (size_t)nxt.pn * tstep : cB;
;         for (int t = 0; t < nt; t += 2) {
;             const bool last = (t == nt - 2);
;             const char* a1 = cA + (size_t)(t + 1) * kstep;
;             const char* a2 = last ? nA : cA + (size_t)(t + 2) * kstep; const char* b2 = last ? nB : cB + (size_t)(t + 2) * kstep;
;     ...
; #pragma unroll
;         for (int a = 0; a < 2; ++a)
; #pragma unroll
;             for (int b = 0; b < 2; ++b)
; #pragma unroll
;                 for (int m = 0; m < 4; ++m)
; #pragma unroll
;                     for (int n = 0; n < 2; ++n) acc[a][b][m][n] = (f32x4){0.f, 0.f, 0.f, 0.f};
.LBB0_404:
	s_ashr_i32 s17, s16, 31
	s_lshl_b64 s[20:21], s[16:17], 19
	s_add_u32 s20, s29, s20
	s_addc_u32 s21, s30, s21
	s_and_b64 s[22:23], s[4:5], exec
	s_cselect_b32 s7, s21, s9
	s_cselect_b32 s17, s20, s8
	s_ashr_i32 s19, s18, 31
	s_lshl_b64 s[22:23], s[18:19], 19
	s_add_u32 s22, s31, s22
	s_addc_u32 s23, s34, s23
	s_and_b64 s[26:27], s[4:5], exec
	s_cselect_b32 s19, s23, s25
	s_cselect_b32 s43, s22, s24
	s_add_u32 s8, s8, 0x40080
	s_addc_u32 s9, s9, 0
	s_add_u32 s44, s24, 0x100
	v_mov_b64_e32 v[4:5], 0
	s_addc_u32 s45, s25, 0
	s_mov_b32 s46, -2
	v_mov_b64_e32 v[6:7], 0
	v_mov_b64_e32 v[8:9], 0
	v_mov_b64_e32 v[10:11], 0
	v_mov_b64_e32 v[12:13], 0
	v_mov_b64_e32 v[14:15], 0
	v_mov_b64_e32 v[16:17], 0
	v_mov_b64_e32 v[18:19], 0
	v_mov_b64_e32 v[20:21], 0
	v_mov_b64_e32 v[22:23], 0
	v_mov_b64_e32 v[24:25], 0
	v_mov_b64_e32 v[26:27], 0
	v_mov_b64_e32 v[28:29], 0
	v_mov_b64_e32 v[30:31], 0
	v_mov_b64_e32 v[32:33], 0
	v_mov_b64_e32 v[34:35], 0
	v_mov_b64_e32 v[36:37], 0
	v_mov_b64_e32 v[38:39], 0
	v_mov_b64_e32 v[40:41], 0
	v_mov_b64_e32 v[42:43], 0
	v_mov_b64_e32 v[44:45], 0
	v_mov_b64_e32 v[46:47], 0
	v_mov_b64_e32 v[48:49], 0
	v_mov_b64_e32 v[50:51], 0
	v_mov_b64_e32 v[52:53], 0
	v_mov_b64_e32 v[54:55], 0
	v_mov_b64_e32 v[56:57], 0
	v_mov_b64_e32 v[58:59], 0
	v_mov_b64_e32 v[60:61], 0
	v_mov_b64_e32 v[62:63], 0
	v_mov_b64_e32 v[64:65], 0
	v_mov_b64_e32 v[66:67], 0
	v_mov_b64_e32 v[68:69], 0
	v_mov_b64_e32 v[70:71], 0
	v_mov_b64_e32 v[72:73], 0
	v_mov_b64_e32 v[74:75], 0
	v_mov_b64_e32 v[76:77], 0
	v_mov_b64_e32 v[78:79], 0
	v_mov_b64_e32 v[80:81], 0
	v_mov_b64_e32 v[82:83], 0
	v_mov_b64_e32 v[84:85], 0
	v_mov_b64_e32 v[86:87], 0
	v_mov_b64_e32 v[88:89], 0
	v_mov_b64_e32 v[90:91], 0
	v_mov_b64_e32 v[92:93], 0
	v_mov_b64_e32 v[94:95], 0
	v_mov_b64_e32 v[96:97], 0
	v_mov_b64_e32 v[98:99], 0
	v_mov_b64_e32 v[100:101], 0
	v_mov_b64_e32 v[102:103], 0
	v_mov_b64_e32 v[104:105], 0
	v_mov_b64_e32 v[106:107], 0
	v_mov_b64_e32 v[108:109], 0
	v_mov_b64_e32 v[110:111], 0
	v_mov_b64_e32 v[112:113], 0
	v_mov_b64_e32 v[114:115], 0
	v_mov_b64_e32 v[116:117], 0
	v_mov_b64_e32 v[118:119], 0
	v_mov_b64_e32 v[120:121], 0
	v_mov_b64_e32 v[122:123], 0
	v_mov_b64_e32 v[124:125], 0
	v_mov_b64_e32 v[126:127], 0
	v_mov_b64_e32 v[128:129], 0
	v_mov_b64_e32 v[130:131], 0

; template <class Epi, class Sched, bool ALIGN_EPI = false, bool SP2 = false>
; __device__ __forceinline__ void gemm_phase(PG8_LAS unsigned char* lds, const Gemm g, const Sched& S, const Epi& E) {
;     ...
;         const bool has_next = S.next(ui + 1, nxt);
;         const char* nA = has_next ? (const char*)g.A + (size_t)nxt.pm * tstep : cA; const char* nB = has_next ? (const char*)g.Bt + (size_t)nxt.pn * tstep : cB;
;         for (int t = 0; t < nt; t += 2) {
;             const bool last = (t == nt - 2);
;             const char* a1 = cA + (size_t)(t + 1) * kstep;
;             const char* a2 = last ? nA : cA + (size_t)(t + 2) * kstep; const char* b2 = last ? nB : cB + (size_t)(t + 2) * kstep;
;     ...
; #pragma unroll
;         for (int a = 0; a < 2; ++a)
; #pragma unroll
;             for (int b = 0; b < 2; ++b)
; #pragma unroll
;                 for (int m = 0; m < 4; ++m)
; #pragma unroll
;                     for (int n = 0; n < 2; ++n) acc[a][b][m][n] = (f32x4){0.f, 0.f, 0.f, 0.f};
.LBB0_479:
	s_add_u32 s44, s28, 0x100
	v_mov_b64_e32 v[4:5], 0
	s_addc_u32 s45, s29, 0
	s_mov_b32 s53, -2
	v_mov_b64_e32 v[6:7], 0
	v_mov_b64_e32 v[8:9], 0
	v_mov_b64_e32 v[10:11], 0
	v_mov_b64_e32 v[12:13], 0
	v_mov_b64_e32 v[14:15], 0
	v_mov_b64_e32 v[16:17], 0
	v_mov_b64_e32 v[18:19], 0
	v_mov_b64_e32 v[20:21], 0
	v_mov_b64_e32 v[22:23], 0
	v_mov_b64_e32 v[24:25], 0
	v_mov_b64_e32 v[26:27], 0
	v_mov_b64_e32 v[28:29], 0
	v_mov_b64_e32 v[30:31], 0
	v_mov_b64_e32 v[32:33], 0
	v_mov_b64_e32 v[34:35], 0
	v_mov_b64_e32 v[36:37], 0
	v_mov_b64_e32 v[38:39], 0
	v_mov_b64_e32 v[40:41], 0
	v_mov_b64_e32 v[42:43], 0
	v_mov_b64_e32 v[44:45], 0
	v_mov_b64_e32 v[46:47], 0
	v_mov_b64_e32 v[48:49], 0
	v_mov_b64_e32 v[50:51], 0
	v_mov_b64_e32 v[52:53], 0
	v_mov_b64_e32 v[54:55], 0
	v_mov_b64_e32 v[56:57], 0
	v_mov_b64_e32 v[58:59], 0
	v_mov_b64_e32 v[60:61], 0
	v_mov_b64_e32 v[62:63], 0
	v_mov_b64_e32 v[64:65], 0
	v_mov_b64_e32 v[66:67], 0
	v_mov_b64_e32 v[72:73], 0
	v_mov_b64_e32 v[74:75], 0
	v_mov_b64_e32 v[76:77], 0
	v_mov_b64_e32 v[78:79], 0
	s_waitcnt vmcnt(0)
	v_mov_b64_e32 v[84:85], 0
	v_mov_b64_e32 v[86:87], 0
	v_mov_b64_e32 v[88:89], 0
	v_mov_b64_e32 v[90:91], 0
	v_mov_b64_e32 v[96:97], 0
	v_mov_b64_e32 v[98:99], 0
	v_mov_b64_e32 v[104:105], 0
	v_mov_b64_e32 v[106:107], 0
	v_mov_b64_e32 v[108:109], 0
	v_mov_b64_e32 v[110:111], 0
	v_mov_b64_e32 v[116:117], 0
	v_mov_b64_e32 v[118:119], 0
	v_mov_b64_e32 v[124:125], 0
	v_mov_b64_e32 v[126:127], 0
	v_mov_b64_e32 v[128:129], 0
	v_mov_b64_e32 v[130:131], 0
	v_mov_b64_e32 v[136:137], 0
	v_mov_b64_e32 v[138:139], 0
	v_mov_b64_e32 v[140:141], 0
	v_mov_b64_e32 v[142:143], 0
	v_mov_b64_e32 v[148:149], 0
	v_mov_b64_e32 v[150:151], 0
	v_mov_b64_e32 v[152:153], 0
	v_mov_b64_e32 v[154:155], 0
	v_mov_b64_e32 v[160:161], 0
	v_mov_b64_e32 v[162:163], 0
	v_mov_b64_e32 v[164:165], 0
	v_mov_b64_e32 v[166:167], 0
